# phase Y: the batch's 64 early-tile sparse-attention items are claimed dynamically (heaviest first) by the batch's workgroups
# speedup vs baseline: 1.1126x; 1.0094x over previous
; __device__ void phase_y(const Params& p, int layer, unsigned char* smem) {
;   constexpr int NI = 8 * 2 * 64;
;   const int G = gridDim.x;
;   for (int i = blockIdx.x; i < NI / 2; i += G) {
; #pragma unroll 1
;     for (int h = 0; h < 2; ++h) {
;       int it = h ? (NI - 1 - i) : i;
;       int qt = 63 - (it >> 4); int r = it & 15; int b = r >> 1, g = r & 1;
;       item_nsa(p, layer, b, g, qt, smem);
;     }
;   }
.LBB0_27:
	v_writelane_b32 v255, s52, 19
	s_add_i32 s0, s52, -1
	s_mul_hi_i32 s1, s0, 0x66666667
	s_lshr_b32 s6, s1, 31
	s_ashr_i32 s1, s1, 1
	s_add_i32 s8, s1, s6
	v_writelane_b32 v255, s53, 20
	s_mov_b32 s6, s8
	s_mul_i32 s1, s8, 5
	v_writelane_b32 v255, s6, 21
	s_sub_i32 s44, s0, s1
	s_mov_b64 s[0:1], -1
	v_writelane_b32 v255, s7, 22
	s_cmp_lt_i32 s44, 2
	s_mov_b64 s[70:71], 0
	s_cbranch_scc1 .LBB0_281
	s_cmp_gt_i32 s44, 2
	v_writelane_b32 v255, s44, 23
	s_cbranch_scc0 .LBB0_192
	s_cmp_eq_u32 s44, 3
	s_mov_b64 s[70:71], -1
	s_cbranch_scc0 .LBB0_191
	v_readlane_b32 s0, v254, 2
	v_readlane_b32 s1, v254, 3
	s_andn2_b64 vcc, exec, s[0:1]
	s_cbranch_vccnz .LBB0_190
	v_readlane_b32 s9, v253, 0
	v_writelane_b32 v255, s87, 62
	v_readlane_b32 s0, v255, 60
	s_cmp_lg_u32 s0, 1
	s_cbranch_scc1 .LBB0_33
	s_mov_b32 s0, 1
	v_writelane_b32 v255, s0, 62
	s_and_b32 s0, s9, 7
	s_lshl_b32 s0, s0, 6
	v_readlane_b32 s1, v255, 21
	s_lshl_b32 s1, s1, 2
	s_add_i32 s0, s0, s1
	s_addk_i32 s0, 0x3600
	s_add_u32 s30, s88, s0
	s_addc_u32 s31, s89, 0
	v_writelane_b32 v255, s30, 54
	v_writelane_b32 v255, s31, 55
	v_cmp_eq_u32_e32 vcc, 0, v210
	s_and_saveexec_b64 s[38:39], vcc
	v_mov_b32_e32 v2, 1
	s_nop 4
	global_atomic_add v211, v1, v2, s[30:31] sc0
	s_or_b64 exec, exec, s[38:39]
	s_branch .LBB0_33

; __device__ __forceinline__ float bf2f(u16 b) { return __uint_as_float(((unsigned)b) << 16); }
; __device__ __forceinline__ float silu_f(float x) { return x * __builtin_amdgcn_rcpf(1.f + __expf(-x)); }
; __device__ void item_nsa(const Params& p, int layer, int b, int g, int qt, unsigned char* smem) {
;     ...
;     for (int i = 0; i < 4; ++i) {
;       const int c = tid + i * 256;
;       const int row = c >> 3, ch = c & 7;
;       gfin[i] = *(const u32x4*)(P_H + ((size_t)b * SEQ + q0 + (row & 31)) * HS + C_GC + (g * 4 + (row >> 5)) * 64 + ch * 8);
;     }
; #pragma unroll
;     for (int n = 0; n < 2; ++n) {
;       float inv = gate[n][1] / l[n];
; #pragma unroll
;       for (int dt = 0; dt < 4; ++dt) {
;         uint2 v = *(const uint2*)(sOf + n * 16 * 72 + dt * 16);
;         float a0 = bf2f((u16)(v.x & 0xffff)) + O[n][dt][0] * inv, a1 = bf2f((u16)(v.x >> 16)) + O[n][dt][1] * inv;
;         float a2 = bf2f((u16)(v.y & 0xffff)) + O[n][dt][2] * inv, a3 = bf2f((u16)(v.y >> 16)) + O[n][dt][3] * inv;
;         uint2 o; o.x = pack2(a0, a1); o.y = pack2(a2, a3);
;         *(uint2*)(sOf + n * 16 * 72 + dt * 16) = o;
;       }
;     }
;   }
;   __syncthreads();
;   {
;     const u16* sRow = (const u16*)sImp;
; #pragma unroll
;     for (int i = 0; i < 4; ++i) {
;       const int c = tid + i * 256;
;       const int row = c >> 3, ch = c & 7;
;       const size_t tok = (size_t)b * SEQ + q0 + (row & 31);
;       const int hcol = (g * 4 + (row >> 5)) * 64 + ch * 8;
;       u32x4 v = *(const u32x4*)(sRow + row * 72 + ch * 8);
;       u32x4 gt = gfin[i];
;       u32x4 o;
; #pragma unroll
;       for (int k = 0; k < 4; ++k) {
;         float x0 = bf2f((u16)(v[k] & 0xffff)) * silu_f(bf2f((u16)(gt[k] & 0xffff)));
;         float x1 = bf2f((u16)(v[k] >> 16)) * silu_f(bf2f((u16)(gt[k] >> 16)));
;         o[k] = pack2(x0, x1);
;       }
;       *(u32x4*)(P_XN + tok * DM + 512 + hcol) = o;
.LBB0_34:
	v_and_b32_e32 v0, 0xffff0000, v202
	v_mul_f32_e32 v0, 0xbfb8aa3b, v0
	v_exp_f32_e32 v0, v0
	s_lshl_b32 s0, s35, 11
	s_ashr_i32 s1, s8, 31
	s_add_u32 s0, s0, s8
	v_add_f32_e32 v0, 1.0, v0
	s_waitcnt vmcnt(1)
	v_rcp_f32_e32 v68, v0
	v_and_b32_e32 v0, 0xffff0000, v191
	v_mul_f32_e32 v0, 0xbfb8aa3b, v0
	v_exp_f32_e32 v0, v0
	v_mov_b64_e32 v[2:3], s[88:89]
	s_addc_u32 s1, 0, s1
	v_and_b32_e32 v37, 56, v193
	v_add_f32_e32 v0, 1.0, v0
	v_rcp_f32_e32 v62, v0
	v_lshrrev_b32_e32 v0, 3, v189
	v_and_or_b32 v0, v0, 31, s0
	v_mad_u64_u32 v[2:3], s[18:19], v0, s3, v[2:3]
	v_mad_i32_i24 v3, s1, v228, v3
	v_lshlrev_b32_e32 v0, 1, v37
	v_ashrrev_i32_e32 v4, 8, v189
	v_lshl_add_u64 v[2:3], v[2:3], 0, v[0:1]
	s_mov_b64 s[18:19], 0x4925c30
	v_add_lshl_u32 v60, s25, v4, 6
	v_lshl_add_u64 v[2:3], v[2:3], 0, s[18:19]
	v_ashrrev_i32_e32 v61, 31, v60
	v_lshl_add_u64 v[4:5], v[60:61], 1, v[2:3]
	global_load_dwordx4 v[14:17], v[4:5], off
	v_add_u32_e32 v61, 0x100, v189
	v_ashrrev_i32_e32 v4, 8, v61
	v_add_lshl_u32 v58, v4, s25, 6
	v_ashrrev_i32_e32 v59, 31, v58
	v_lshl_add_u64 v[4:5], v[58:59], 1, v[2:3]
	v_add_u32_e32 v57, 0x200, v189
	global_load_dwordx4 v[10:13], v[4:5], off
	v_ashrrev_i32_e32 v4, 8, v57
	v_add_lshl_u32 v38, v4, s25, 6
	v_ashrrev_i32_e32 v39, 31, v38
	v_lshl_add_u64 v[4:5], v[38:39], 1, v[2:3]
	v_add_u32_e32 v39, 0x300, v189
	global_load_dwordx4 v[6:9], v[4:5], off
	v_ashrrev_i32_e32 v4, 8, v39
	v_add_lshl_u32 v18, v4, s25, 6
	v_ashrrev_i32_e32 v19, 31, v18
	v_lshl_add_u64 v[2:3], v[18:19], 1, v[2:3]
	v_div_scale_f32 v19, s[18:19], v56, v56, v62
	v_rcp_f32_e32 v59, v19
	s_movk_i32 s8, 0x90
	global_load_dwordx4 v[2:5], v[2:3], off
	s_movk_i32 s15, 0x90
	v_fma_f32 v63, -v19, v59, 1.0
	v_fmac_f32_e32 v59, v63, v59
	v_div_scale_f32 v63, vcc, v62, v56, v62
	v_mul_f32_e32 v64, v63, v59
	v_fma_f32 v65, -v19, v64, v63
	v_fmac_f32_e32 v64, v65, v59
	v_fma_f32 v19, -v19, v64, v63
	v_div_fmas_f32 v19, v19, v59, v64
	v_div_fixup_f32 v56, v19, v56, v62
	ds_read2_b64 v[62:65], v151 offset1:4
	v_div_scale_f32 v19, s[18:19], v36, v36, v68
	s_waitcnt lgkmcnt(0)
	v_lshlrev_b32_e32 v66, 16, v62
	v_and_b32_e32 v67, 0xffff0000, v62
	v_lshlrev_b32_e32 v62, 16, v63
	v_and_b32_e32 v63, 0xffff0000, v63
	v_pk_fma_f32 v[52:53], v[52:53], v[56:57], v[66:67] op_sel_hi:[1,0,1]
	v_pk_fma_f32 v[54:55], v[54:55], v[56:57], v[62:63] op_sel_hi:[1,0,1]
	v_cvt_pk_bf16_f32 v52, v52, v53
	v_cvt_pk_bf16_f32 v53, v54, v55
	v_lshlrev_b32_e32 v54, 16, v64
	v_and_b32_e32 v55, 0xffff0000, v64
	v_pk_fma_f32 v[48:49], v[48:49], v[56:57], v[54:55] op_sel_hi:[1,0,1]
	v_lshlrev_b32_e32 v54, 16, v65
	v_and_b32_e32 v55, 0xffff0000, v65
	v_pk_fma_f32 v[50:51], v[50:51], v[56:57], v[54:55] op_sel_hi:[1,0,1]
	v_cvt_pk_bf16_f32 v48, v48, v49
	v_cvt_pk_bf16_f32 v49, v50, v51
	ds_write2_b64 v151, v[52:53], v[48:49] offset1:4
	ds_read2_b64 v[48:51], v151 offset0:8 offset1:12
	s_waitcnt lgkmcnt(0)
	v_lshlrev_b32_e32 v52, 16, v48
	v_and_b32_e32 v53, 0xffff0000, v48
	v_lshlrev_b32_e32 v48, 16, v49
	v_and_b32_e32 v49, 0xffff0000, v49
	v_pk_fma_f32 v[44:45], v[44:45], v[56:57], v[52:53] op_sel_hi:[1,0,1]
	v_pk_fma_f32 v[46:47], v[46:47], v[56:57], v[48:49] op_sel_hi:[1,0,1]
	v_cvt_pk_bf16_f32 v44, v44, v45
	v_cvt_pk_bf16_f32 v45, v46, v47
	v_lshlrev_b32_e32 v46, 16, v50
	v_and_b32_e32 v47, 0xffff0000, v50
	v_pk_fma_f32 v[40:41], v[40:41], v[56:57], v[46:47] op_sel_hi:[1,0,1]
	v_lshlrev_b32_e32 v46, 16, v51
	v_and_b32_e32 v47, 0xffff0000, v51
	v_pk_fma_f32 v[42:43], v[42:43], v[56:57], v[46:47] op_sel_hi:[1,0,1]
	v_cvt_pk_bf16_f32 v40, v40, v41
	v_cvt_pk_bf16_f32 v41, v42, v43
	ds_write2_b64 v151, v[44:45], v[40:41] offset0:8 offset1:12
	v_rcp_f32_e32 v40, v19
	s_nop 0
	v_fma_f32 v41, -v19, v40, 1.0
	v_fmac_f32_e32 v40, v41, v40
	v_div_scale_f32 v41, vcc, v68, v36, v68
	v_mul_f32_e32 v42, v41, v40
	v_fma_f32 v43, -v19, v42, v41
	v_fmac_f32_e32 v42, v43, v40
	v_fma_f32 v19, -v19, v42, v41
	v_div_fmas_f32 v19, v19, v40, v42
	ds_read2_b64 v[40:43], v150 offset0:32 offset1:36
	v_div_fixup_f32 v36, v19, v36, v68
	v_ashrrev_i32_e32 v19, 3, v189
	s_waitcnt lgkmcnt(0)
	v_lshlrev_b32_e32 v44, 16, v40
	v_and_b32_e32 v45, 0xffff0000, v40
	v_lshlrev_b32_e32 v40, 16, v41
	v_and_b32_e32 v41, 0xffff0000, v41
	v_pk_fma_f32 v[32:33], v[32:33], v[36:37], v[44:45] op_sel_hi:[1,0,1]
	v_pk_fma_f32 v[34:35], v[34:35], v[36:37], v[40:41] op_sel_hi:[1,0,1]
	v_cvt_pk_bf16_f32 v32, v32, v33
	v_cvt_pk_bf16_f32 v33, v34, v35
	v_lshlrev_b32_e32 v34, 16, v42
	v_and_b32_e32 v35, 0xffff0000, v42
	v_pk_fma_f32 v[28:29], v[28:29], v[36:37], v[34:35] op_sel_hi:[1,0,1]
	v_lshlrev_b32_e32 v34, 16, v43
	v_and_b32_e32 v35, 0xffff0000, v43
	v_pk_fma_f32 v[30:31], v[30:31], v[36:37], v[34:35] op_sel_hi:[1,0,1]
	v_cvt_pk_bf16_f32 v28, v28, v29
	v_cvt_pk_bf16_f32 v29, v30, v31
	ds_write2_b64 v150, v[32:33], v[28:29] offset0:32 offset1:36
	ds_read2_b64 v[28:31], v150 offset0:40 offset1:44
	s_waitcnt lgkmcnt(0)
	v_lshlrev_b32_e32 v32, 16, v28
	v_and_b32_e32 v33, 0xffff0000, v28
	v_lshlrev_b32_e32 v28, 16, v29
	v_and_b32_e32 v29, 0xffff0000, v29
	v_pk_fma_f32 v[24:25], v[24:25], v[36:37], v[32:33] op_sel_hi:[1,0,1]
	v_pk_fma_f32 v[26:27], v[26:27], v[36:37], v[28:29] op_sel_hi:[1,0,1]
	v_cvt_pk_bf16_f32 v24, v24, v25
	v_cvt_pk_bf16_f32 v25, v26, v27
	v_lshlrev_b32_e32 v26, 16, v30
	v_and_b32_e32 v27, 0xffff0000, v30
	v_pk_fma_f32 v[20:21], v[20:21], v[36:37], v[26:27] op_sel_hi:[1,0,1]
	v_lshlrev_b32_e32 v26, 16, v31
	v_and_b32_e32 v27, 0xffff0000, v31
	v_pk_fma_f32 v[22:23], v[22:23], v[36:37], v[26:27] op_sel_hi:[1,0,1]
	v_cvt_pk_bf16_f32 v20, v20, v21
	v_cvt_pk_bf16_f32 v21, v22, v23
	ds_write2_b64 v150, v[24:25], v[20:21] offset0:40 offset1:44
	s_waitcnt vmcnt(3)
	v_lshlrev_b32_e32 v24, 16, v14
	v_and_b32_e32 v25, 0xffff0000, v14
	v_mul_f32_e32 v14, 0xbfb8aa3b, v24
	v_exp_f32_e32 v14, v14
	v_mad_u64_u32 v[20:21], s[18:19], v19, s8, v[0:1]
	s_waitcnt lgkmcnt(0)
	v_add_f32_e32 v14, 1.0, v14
	v_rcp_f32_e32 v26, v14
	v_mul_f32_e32 v14, 0xbfb8aa3b, v25
	v_exp_f32_e32 v14, v14
	s_barrier
; __device__ __forceinline__ float bf2f(u16 b) { return __uint_as_float(((unsigned)b) << 16); }
; __device__ __forceinline__ float silu_f(float x) { return x * __builtin_amdgcn_rcpf(1.f + __expf(-x)); }
; __device__ void item_nsa(const Params& p, int layer, int b, int g, int qt, unsigned char* smem) {
;     ...
;   __syncthreads();
;   {
;     const u16* sRow = (const u16*)sImp;
; #pragma unroll
;     for (int i = 0; i < 4; ++i) {
;       const int c = tid + i * 256;
;       const int row = c >> 3, ch = c & 7;
;       const size_t tok = (size_t)b * SEQ + q0 + (row & 31);
;       const int hcol = (g * 4 + (row >> 5)) * 64 + ch * 8;
;       u32x4 v = *(const u32x4*)(sRow + row * 72 + ch * 8);
;       u32x4 gt = gfin[i];
;       u32x4 o;
; #pragma unroll
;       for (int k = 0; k < 4; ++k) {
;         float x0 = bf2f((u16)(v[k] & 0xffff)) * silu_f(bf2f((u16)(gt[k] & 0xffff)));
;         float x1 = bf2f((u16)(v[k] >> 16)) * silu_f(bf2f((u16)(gt[k] >> 16)));
;         o[k] = pack2(x0, x1);
;       }
;       *(u32x4*)(P_XN + tok * DM + 512 + hcol) = o;
;     }
	ds_read_b128 v[20:23], v20 offset:36864
	v_add_f32_e32 v14, 1.0, v14
	v_rcp_f32_e32 v27, v14
	s_waitcnt lgkmcnt(0)
	v_lshlrev_b32_e32 v28, 16, v20
	v_and_b32_e32 v29, 0xffff0000, v20
	v_pk_mul_f32 v[24:25], v[26:27], v[24:25]
	v_lshlrev_b32_e32 v26, 16, v21
	v_pk_mul_f32 v[24:25], v[24:25], v[28:29]
	v_and_b32_e32 v27, 0xffff0000, v21
	v_cvt_pk_bf16_f32 v14, v24, v25
	v_lshlrev_b32_e32 v24, 16, v15
	v_and_b32_e32 v25, 0xffff0000, v15
	v_mul_f32_e32 v15, 0xbfb8aa3b, v24
	v_exp_f32_e32 v15, v15
	s_nop 0
	v_add_f32_e32 v15, 1.0, v15
	v_rcp_f32_e32 v20, v15
	v_mul_f32_e32 v15, 0xbfb8aa3b, v25
	v_exp_f32_e32 v15, v15
	s_nop 0
	v_add_f32_e32 v15, 1.0, v15
	v_rcp_f32_e32 v21, v15
	s_nop 0
	v_pk_mul_f32 v[20:21], v[20:21], v[24:25]
	s_nop 0
	v_pk_mul_f32 v[20:21], v[20:21], v[26:27]
	v_lshlrev_b32_e32 v26, 16, v22
	v_cvt_pk_bf16_f32 v15, v20, v21
	v_lshlrev_b32_e32 v20, 16, v16
	v_and_b32_e32 v21, 0xffff0000, v16
	v_mul_f32_e32 v16, 0xbfb8aa3b, v20
	v_exp_f32_e32 v16, v16
	v_and_b32_e32 v27, 0xffff0000, v22
	v_add_f32_e32 v16, 1.0, v16
	v_rcp_f32_e32 v24, v16
	v_mul_f32_e32 v16, 0xbfb8aa3b, v21
	v_exp_f32_e32 v16, v16
	s_nop 0
	v_add_f32_e32 v16, 1.0, v16
	v_rcp_f32_e32 v25, v16
	s_nop 0
	v_pk_mul_f32 v[20:21], v[24:25], v[20:21]
	s_nop 0
	v_pk_mul_f32 v[20:21], v[20:21], v[26:27]
	v_lshlrev_b32_e32 v24, 16, v23
	v_cvt_pk_bf16_f32 v16, v20, v21
	v_lshlrev_b32_e32 v20, 16, v17
	v_and_b32_e32 v21, 0xffff0000, v17
	v_mul_f32_e32 v17, 0xbfb8aa3b, v20
	v_exp_f32_e32 v17, v17
	v_and_b32_e32 v25, 0xffff0000, v23
	v_add_f32_e32 v17, 1.0, v17
	v_rcp_f32_e32 v22, v17
	v_mul_f32_e32 v17, 0xbfb8aa3b, v21
	v_exp_f32_e32 v17, v17
	s_nop 0
	v_add_f32_e32 v17, 1.0, v17
	v_rcp_f32_e32 v23, v17
	s_nop 0
	v_pk_mul_f32 v[20:21], v[22:23], v[20:21]
	s_nop 0
	v_pk_mul_f32 v[20:21], v[20:21], v[24:25]
	v_or_b32_e32 v22, v60, v37
	v_cvt_pk_bf16_f32 v17, v20, v21
	v_and_or_b32 v20, v19, 31, s0
	v_mov_b32_e32 v21, s1
	v_lshlrev_b64 v[24:25], 11, v[20:21]
	v_lshl_add_u64 v[24:25], s[88:89], 0, v[24:25]
	v_ashrrev_i32_e32 v23, 31, v22
	v_lshl_add_u64 v[22:23], v[22:23], 1, v[24:25]
	s_mov_b32 s1, 0x2924000
	v_add_co_u32_e32 v22, vcc, s1, v22
	v_ashrrev_i32_e32 v19, 3, v61
	s_nop 0
	v_addc_co_u32_e32 v23, vcc, 0, v23, vcc
	global_store_dwordx4 v[22:23], v[14:17], off offset:2048
	s_waitcnt vmcnt(3)
	v_lshlrev_b32_e32 v22, 16, v10
	v_and_b32_e32 v23, 0xffff0000, v10
	v_mul_f32_e32 v10, 0xbfb8aa3b, v22
	v_exp_f32_e32 v10, v10
	v_mad_u64_u32 v[14:15], s[18:19], v19, s8, v[0:1]
	ds_read_b128 v[14:17], v14 offset:36864
	v_add_f32_e32 v10, 1.0, v10
	v_rcp_f32_e32 v24, v10
	v_mul_f32_e32 v10, 0xbfb8aa3b, v23
	v_exp_f32_e32 v10, v10
	s_waitcnt lgkmcnt(0)
	v_lshlrev_b32_e32 v26, 16, v14
	v_and_b32_e32 v27, 0xffff0000, v14
	v_and_or_b32 v20, v19, 31, s0
	v_add_f32_e32 v10, 1.0, v10
	v_rcp_f32_e32 v25, v10
	v_ashrrev_i32_e32 v19, 3, v57
	v_pk_mul_f32 v[22:23], v[24:25], v[22:23]
	s_nop 0
	v_pk_mul_f32 v[22:23], v[22:23], v[26:27]
	v_lshlrev_b32_e32 v24, 16, v15
	v_cvt_pk_bf16_f32 v10, v22, v23
	v_lshlrev_b32_e32 v22, 16, v11
	v_and_b32_e32 v23, 0xffff0000, v11
	v_mul_f32_e32 v11, 0xbfb8aa3b, v22
	v_exp_f32_e32 v11, v11
	v_and_b32_e32 v25, 0xffff0000, v15
	v_add_f32_e32 v11, 1.0, v11
	v_rcp_f32_e32 v14, v11
	v_mul_f32_e32 v11, 0xbfb8aa3b, v23
	v_exp_f32_e32 v11, v11
	s_nop 0
	v_add_f32_e32 v11, 1.0, v11
	v_rcp_f32_e32 v15, v11
	s_nop 0
	v_pk_mul_f32 v[14:15], v[14:15], v[22:23]
	s_nop 0
	v_pk_mul_f32 v[14:15], v[14:15], v[24:25]
	v_lshlrev_b32_e32 v24, 16, v16
	v_cvt_pk_bf16_f32 v11, v14, v15
	v_lshlrev_b32_e32 v14, 16, v12
	v_and_b32_e32 v15, 0xffff0000, v12
	v_mul_f32_e32 v12, 0xbfb8aa3b, v14
	v_exp_f32_e32 v12, v12
	v_and_b32_e32 v25, 0xffff0000, v16
	v_add_f32_e32 v12, 1.0, v12
	v_rcp_f32_e32 v22, v12
	v_mul_f32_e32 v12, 0xbfb8aa3b, v15
	v_exp_f32_e32 v12, v12
	s_nop 0
	v_add_f32_e32 v12, 1.0, v12
	v_rcp_f32_e32 v23, v12
	s_nop 0
	v_pk_mul_f32 v[14:15], v[22:23], v[14:15]
	s_nop 0
	v_pk_mul_f32 v[14:15], v[14:15], v[24:25]
	v_lshlrev_b32_e32 v22, 16, v17
	v_cvt_pk_bf16_f32 v12, v14, v15
	v_lshlrev_b32_e32 v14, 16, v13
	v_and_b32_e32 v15, 0xffff0000, v13
	v_mul_f32_e32 v13, 0xbfb8aa3b, v14
	v_exp_f32_e32 v13, v13
	v_and_b32_e32 v23, 0xffff0000, v17
	v_add_f32_e32 v13, 1.0, v13
	v_rcp_f32_e32 v16, v13
	v_mul_f32_e32 v13, 0xbfb8aa3b, v15
	v_exp_f32_e32 v13, v13
	s_nop 0
	v_add_f32_e32 v13, 1.0, v13
	v_rcp_f32_e32 v17, v13
	s_nop 0
	v_pk_mul_f32 v[14:15], v[16:17], v[14:15]
	s_nop 0
	v_pk_mul_f32 v[14:15], v[14:15], v[22:23]
	v_lshlrev_b64 v[16:17], 11, v[20:21]
	v_cvt_pk_bf16_f32 v13, v14, v15
	v_or_b32_e32 v14, v58, v37
	v_lshl_add_u64 v[16:17], s[88:89], 0, v[16:17]
	v_ashrrev_i32_e32 v15, 31, v14
	v_lshl_add_u64 v[14:15], v[14:15], 1, v[16:17]
	v_add_co_u32_e32 v14, vcc, s1, v14
	v_and_or_b32 v20, v19, 31, s0
	s_nop 0
	v_addc_co_u32_e32 v15, vcc, 0, v15, vcc
	global_store_dwordx4 v[14:15], v[10:13], off offset:2048
	s_waitcnt vmcnt(3)
; __device__ __forceinline__ float bf2f(u16 b) { return __uint_as_float(((unsigned)b) << 16); }
; __device__ __forceinline__ float silu_f(float x) { return x * __builtin_amdgcn_rcpf(1.f + __expf(-x)); }
; __device__ void item_nsa(const Params& p, int layer, int b, int g, int qt, unsigned char* smem) {
;     ...
;   {
;     const u16* sRow = (const u16*)sImp;
; #pragma unroll
;     for (int i = 0; i < 4; ++i) {
;       const int c = tid + i * 256;
;       const int row = c >> 3, ch = c & 7;
;       const size_t tok = (size_t)b * SEQ + q0 + (row & 31);
;       const int hcol = (g * 4 + (row >> 5)) * 64 + ch * 8;
;       u32x4 v = *(const u32x4*)(sRow + row * 72 + ch * 8);
;       u32x4 gt = gfin[i];
;       u32x4 o;
; #pragma unroll
;       for (int k = 0; k < 4; ++k) {
;         float x0 = bf2f((u16)(v[k] & 0xffff)) * silu_f(bf2f((u16)(gt[k] & 0xffff)));
;         float x1 = bf2f((u16)(v[k] >> 16)) * silu_f(bf2f((u16)(gt[k] >> 16)));
;         o[k] = pack2(x0, x1);
;       }
;       *(u32x4*)(P_XN + tok * DM + 512 + hcol) = o;
;     }
; __device__ void phase_y(const Params& p, int layer, unsigned char* smem) {
;     ...
;   for (int i = blockIdx.x; i < NI / 2; i += G) {
; #pragma unroll 1
;     for (int h = 0; h < 2; ++h) {
;       int it = h ? (NI - 1 - i) : i;
;       int qt = 63 - (it >> 4); int r = it & 15; int b = r >> 1, g = r & 1;
;       item_nsa(p, layer, b, g, qt, smem);
;     }
	v_lshlrev_b32_e32 v14, 16, v6
	v_and_b32_e32 v15, 0xffff0000, v6
	v_mul_f32_e32 v6, 0xbfb8aa3b, v14
	v_exp_f32_e32 v6, v6
	v_mad_u64_u32 v[10:11], s[18:19], v19, s8, v[0:1]
	ds_read_b128 v[10:13], v10 offset:36864
	v_add_f32_e32 v6, 1.0, v6
	v_rcp_f32_e32 v16, v6
	v_mul_f32_e32 v6, 0xbfb8aa3b, v15
	v_exp_f32_e32 v6, v6
	s_waitcnt lgkmcnt(0)
	v_lshlrev_b32_e32 v22, 16, v10
	v_and_b32_e32 v23, 0xffff0000, v10
	v_add_f32_e32 v6, 1.0, v6
	v_rcp_f32_e32 v17, v6
	s_nop 0
	v_pk_mul_f32 v[14:15], v[16:17], v[14:15]
	s_nop 0
	v_pk_mul_f32 v[14:15], v[14:15], v[22:23]
	v_lshlrev_b32_e32 v16, 16, v11
	v_cvt_pk_bf16_f32 v6, v14, v15
	v_lshlrev_b32_e32 v14, 16, v7
	v_and_b32_e32 v15, 0xffff0000, v7
	v_mul_f32_e32 v7, 0xbfb8aa3b, v14
	v_exp_f32_e32 v7, v7
	v_and_b32_e32 v17, 0xffff0000, v11
	v_add_f32_e32 v7, 1.0, v7
	v_rcp_f32_e32 v10, v7
	v_mul_f32_e32 v7, 0xbfb8aa3b, v15
	v_exp_f32_e32 v7, v7
	s_nop 0
	v_add_f32_e32 v7, 1.0, v7
	v_rcp_f32_e32 v11, v7
	s_nop 0
	v_pk_mul_f32 v[10:11], v[10:11], v[14:15]
	s_nop 0
	v_pk_mul_f32 v[10:11], v[10:11], v[16:17]
	v_lshlrev_b32_e32 v16, 16, v12
	v_cvt_pk_bf16_f32 v7, v10, v11
	v_lshlrev_b32_e32 v10, 16, v8
	v_and_b32_e32 v11, 0xffff0000, v8
	v_mul_f32_e32 v8, 0xbfb8aa3b, v10
	v_exp_f32_e32 v8, v8
	v_and_b32_e32 v17, 0xffff0000, v12
	v_add_f32_e32 v8, 1.0, v8
	v_rcp_f32_e32 v14, v8
	v_mul_f32_e32 v8, 0xbfb8aa3b, v11
	v_exp_f32_e32 v8, v8
	s_nop 0
	v_add_f32_e32 v8, 1.0, v8
	v_rcp_f32_e32 v15, v8
	s_nop 0
	v_pk_mul_f32 v[10:11], v[14:15], v[10:11]
	s_nop 0
	v_pk_mul_f32 v[10:11], v[10:11], v[16:17]
	v_lshlrev_b32_e32 v14, 16, v13
	v_cvt_pk_bf16_f32 v8, v10, v11
	v_lshlrev_b32_e32 v10, 16, v9
	v_and_b32_e32 v11, 0xffff0000, v9
	v_mul_f32_e32 v9, 0xbfb8aa3b, v10
	v_exp_f32_e32 v9, v9
	v_and_b32_e32 v15, 0xffff0000, v13
	v_ashrrev_i32_e32 v16, 3, v39
	v_add_f32_e32 v9, 1.0, v9
	v_rcp_f32_e32 v12, v9
	v_mul_f32_e32 v9, 0xbfb8aa3b, v11
	v_exp_f32_e32 v9, v9
	s_nop 0
	v_add_f32_e32 v9, 1.0, v9
	v_rcp_f32_e32 v13, v9
	s_nop 0
	v_pk_mul_f32 v[10:11], v[12:13], v[10:11]
	s_nop 0
	v_pk_mul_f32 v[10:11], v[10:11], v[14:15]
	v_lshlrev_b64 v[12:13], 11, v[20:21]
	v_cvt_pk_bf16_f32 v9, v10, v11
	v_or_b32_e32 v10, v38, v37
	v_lshl_add_u64 v[12:13], s[88:89], 0, v[12:13]
	v_ashrrev_i32_e32 v11, 31, v10
	v_lshl_add_u64 v[10:11], v[10:11], 1, v[12:13]
	v_add_co_u32_e32 v10, vcc, s1, v10
	v_and_or_b32 v20, v16, 31, s0
	s_nop 0
	v_addc_co_u32_e32 v11, vcc, 0, v11, vcc
	global_store_dwordx4 v[10:11], v[6:9], off offset:2048
	s_waitcnt vmcnt(3)
	v_lshlrev_b32_e32 v10, 16, v2
	v_and_b32_e32 v11, 0xffff0000, v2
	v_mad_u64_u32 v[6:7], s[18:19], v16, s8, v[0:1]
	v_mul_f32_e32 v0, 0xbfb8aa3b, v10
	v_exp_f32_e32 v0, v0
	ds_read_b128 v[6:9], v6 offset:36864
	s_mov_b64 s[0:1], 0
	v_add_f32_e32 v0, 1.0, v0
	v_rcp_f32_e32 v12, v0
	v_mul_f32_e32 v0, 0xbfb8aa3b, v11
	v_exp_f32_e32 v0, v0
	s_waitcnt lgkmcnt(0)
	v_lshlrev_b32_e32 v14, 16, v6
	v_and_b32_e32 v15, 0xffff0000, v6
	v_add_f32_e32 v0, 1.0, v0
	v_rcp_f32_e32 v13, v0
	s_nop 0
	v_pk_mul_f32 v[10:11], v[12:13], v[10:11]
	s_nop 0
	v_pk_mul_f32 v[10:11], v[10:11], v[14:15]
	v_lshlrev_b32_e32 v12, 16, v7
	v_cvt_pk_bf16_f32 v2, v10, v11
	v_lshlrev_b32_e32 v10, 16, v3
	v_mul_f32_e32 v0, 0xbfb8aa3b, v10
	v_exp_f32_e32 v0, v0
	v_and_b32_e32 v11, 0xffff0000, v3
	v_and_b32_e32 v13, 0xffff0000, v7
	v_add_f32_e32 v0, 1.0, v0
	v_rcp_f32_e32 v6, v0
	v_mul_f32_e32 v0, 0xbfb8aa3b, v11
	v_exp_f32_e32 v0, v0
	s_nop 0
	v_add_f32_e32 v0, 1.0, v0
	v_rcp_f32_e32 v7, v0
	s_nop 0
	v_pk_mul_f32 v[6:7], v[6:7], v[10:11]
	s_nop 0
	v_pk_mul_f32 v[6:7], v[6:7], v[12:13]
	v_lshlrev_b32_e32 v12, 16, v8
	v_cvt_pk_bf16_f32 v3, v6, v7
	v_lshlrev_b32_e32 v6, 16, v4
	v_mul_f32_e32 v0, 0xbfb8aa3b, v6
	v_exp_f32_e32 v0, v0
	v_and_b32_e32 v7, 0xffff0000, v4
	v_and_b32_e32 v13, 0xffff0000, v8
	v_add_f32_e32 v0, 1.0, v0
	v_rcp_f32_e32 v10, v0
	v_mul_f32_e32 v0, 0xbfb8aa3b, v7
	v_exp_f32_e32 v0, v0
	s_nop 0
	v_add_f32_e32 v0, 1.0, v0
	v_rcp_f32_e32 v11, v0
	s_nop 0
	v_pk_mul_f32 v[6:7], v[10:11], v[6:7]
	s_nop 0
	v_pk_mul_f32 v[6:7], v[6:7], v[12:13]
	v_lshlrev_b32_e32 v10, 16, v9
	v_cvt_pk_bf16_f32 v4, v6, v7
	v_lshlrev_b32_e32 v6, 16, v5
	v_mul_f32_e32 v0, 0xbfb8aa3b, v6
	v_exp_f32_e32 v0, v0
	v_and_b32_e32 v7, 0xffff0000, v5
	v_and_b32_e32 v11, 0xffff0000, v9
	v_add_f32_e32 v0, 1.0, v0
	v_rcp_f32_e32 v8, v0
	v_mul_f32_e32 v0, 0xbfb8aa3b, v7
	v_exp_f32_e32 v0, v0
	s_nop 0
	v_add_f32_e32 v0, 1.0, v0
	v_rcp_f32_e32 v9, v0
	s_nop 0
	v_pk_mul_f32 v[6:7], v[8:9], v[6:7]
	s_nop 0
	v_pk_mul_f32 v[6:7], v[6:7], v[10:11]
	v_lshlrev_b64 v[8:9], 11, v[20:21]
	v_cvt_pk_bf16_f32 v5, v6, v7
	v_or_b32_e32 v6, v18, v37
	v_lshl_add_u64 v[8:9], s[88:89], 0, v[8:9]
	v_ashrrev_i32_e32 v7, 31, v6
	v_lshl_add_u64 v[6:7], v[6:7], 1, v[8:9]
	v_add_co_u32_e32 v6, vcc, 0x2924000, v6
	s_nop 1
	v_addc_co_u32_e32 v7, vcc, 0, v7, vcc
	s_and_b64 vcc, exec, s[6:7]
	global_store_dwordx4 v[6:7], v[2:5], off offset:2048
	v_readlane_b32 s38, v255, 62
	s_cmp_lg_u32 s38, 0
	s_cbranch_scc1 .Lnsa_next
	s_cbranch_vccnz .LBB0_32

; __device__ void phase_y(const Params& p, int layer, unsigned char* smem) {
;     ...
;   for (int i = blockIdx.x; i < NI / 2; i += G) {
; #pragma unroll 1
;     for (int h = 0; h < 2; ++h) {
;       int it = h ? (NI - 1 - i) : i;
;       int qt = 63 - (it >> 4); int r = it & 15; int b = r >> 1, g = r & 1;
;       item_nsa(p, layer, b, g, qt, smem);
;     }
.Lnsa_next:
	v_cmp_eq_u32_e32 vcc, 0, v210
	s_and_saveexec_b64 s[38:39], vcc
	s_cbranch_execz .Lnsa_n1
	s_waitcnt vmcnt(0)
	v_mov_b32_e32 v0, 0x13110
	ds_write_b32 v0, v211
	v_readlane_b32 s30, v255, 54
	v_readlane_b32 s31, v255, 55
	v_mov_b32_e32 v2, 1
	s_nop 4
	global_atomic_add v211, v1, v2, s[30:31] sc0
	s_waitcnt lgkmcnt(0)
.Lnsa_n1:
	s_or_b64 exec, exec, s[38:39]
	s_barrier
	v_mov_b32_e32 v0, 0x13110
	ds_read_b32 v0, v0
	s_waitcnt lgkmcnt(0)
	v_readfirstlane_b32 s38, v0
	s_cmp_gt_u32 s38, 63
	s_cbranch_scc1 .LBB0_190
	s_lshr_b32 s39, s38, 1
	s_add_i32 s39, s39, 32
	s_lshl_b32 s39, s39, 4
	s_and_b32 s38, s38, 1
	s_or_b32 s38, s38, s39
	v_readlane_b32 s39, v253, 0
	s_and_b32 s39, s39, 7
	s_lshl_b32 s39, s39, 1
	s_or_b32 s38, s38, s39
	v_writelane_b32 v255, s38, 24
	s_mov_b64 s[0:1], 0
	s_branch .LBB0_35
